# attention softmax exp/row-sum/cvt section rewritten with scalar f32 ops (no v_pk_mov/v_pk_add shuffles, 8-wide groups), plus s_setprio 1 for waves 0-3 in the prompt loop
# speedup vs baseline: 1.0081x; 1.0064x over previous
; #define LAS __attribute__((address_space(3)))
; __device__ __forceinline__ unsigned pk2(float lo, float hi) { f32x2 v = {lo, hi}; bf16x2_t b = __builtin_convertvector(v, bf16x2_t); return __builtin_bit_cast(unsigned, b); }
; #define MFMA32(a, b, c) __builtin_amdgcn_mfma_f32_32x32x16_bf16((a), (b), (c), 0, 0, 0)
; __device__ __forceinline__ void unit(LAS unsigned char* lds, const Tensors& T, int h, int qrow0, int nact, bool sample, int limbase, int kv0, int kvnew, int nt) {
;     ...
;             { float ps = 0.f;
; #pragma unroll
;               for (int r = 0; r < 16; ++r) { p0[r] = __builtin_amdgcn_exp2f(p0[r] - mrun); p1[r] = __builtin_amdgcn_exp2f(p1[r] - mrun); ps += p0[r] + p1[r]; }
;               lrun += ps; }
;             const LAS unsigned char* vp = lds + OFF_V + buf * VBUF + r32 * VP + hi * 16;
;             { u32x4 vf[2][4];
; #pragma unroll
;               for (int d = 0; d < 4; ++d) vf[0][d] = *(const LAS u32x4*)(vp + d * 32 * VP);
; #pragma unroll
;               for (int j = 0; j < 4; ++j) {
;                   if (j < 3) {
; #pragma unroll
;                       for (int d = 0; d < 4; ++d) vf[(j + 1) & 1][d] = *(const LAS u32x4*)(vp + d * 32 * VP + (j + 1) * 32); }
;                   u32x4 pw;
;                   if (j == 0) { pw.x = pk2(p0[0], p0[1]); pw.y = pk2(p0[2], p0[3]); pw.z = pk2(p0[4], p0[5]); pw.w = pk2(p0[6], p0[7]); }
;                   else if (j == 1) { pw.x = pk2(p0[8], p0[9]); pw.y = pk2(p0[10], p0[11]); pw.z = pk2(p0[12], p0[13]); pw.w = pk2(p0[14], p0[15]); }
;                   else if (j == 2) { pw.x = pk2(p1[0], p1[1]); pw.y = pk2(p1[2], p1[3]); pw.z = pk2(p1[4], p1[5]); pw.w = pk2(p1[6], p1[7]); }
;                   else { pw.x = pk2(p1[8], p1[9]); pw.y = pk2(p1[10], p1[11]); pw.z = pk2(p1[12], p1[13]); pw.w = pk2(p1[14], p1[15]); }
;                   const bf16x8 pa = __builtin_bit_cast(bf16x8, pw);
;                   __builtin_amdgcn_sched_barrier(0);
; #pragma unroll
;                   for (int d = 0; d < 4; ++d) o[d] = MFMA32(pa, __builtin_bit_cast(bf16x8, vf[j & 1][d]), o[d]);
;                   __builtin_amdgcn_sched_barrier(0);
;               } }
.LBB0_911:
	v_sub_f32_e32 v242, v72, v222
	v_sub_f32_e32 v243, v73, v222
	v_sub_f32_e32 v244, v74, v222
	v_sub_f32_e32 v245, v75, v222
	v_sub_f32_e32 v246, v76, v222
	v_sub_f32_e32 v247, v77, v222
	v_sub_f32_e32 v248, v78, v222
	v_sub_f32_e32 v249, v79, v222
	v_exp_f32_e32 v242, v242
	v_exp_f32_e32 v243, v243
	v_exp_f32_e32 v244, v244
	v_exp_f32_e32 v245, v245
	v_exp_f32_e32 v246, v246
	v_exp_f32_e32 v247, v247
	v_exp_f32_e32 v248, v248
	v_exp_f32_e32 v249, v249
	v_cvt_pk_bf16_f32 v232, v242, v243
	v_cvt_pk_bf16_f32 v233, v244, v245
	v_cvt_pk_bf16_f32 v234, v246, v247
	v_cvt_pk_bf16_f32 v235, v248, v249
	v_add_f32_e32 v242, v242, v243
	v_add_f32_e32 v244, v244, v245
	v_add_f32_e32 v246, v246, v247
	v_add_f32_e32 v248, v248, v249
	v_add_f32_e32 v242, v242, v244
	v_add_f32_e32 v246, v246, v248
	v_add_f32_e32 v241, v242, v246
	v_sub_f32_e32 v242, v64, v222
	v_sub_f32_e32 v243, v65, v222
	v_sub_f32_e32 v244, v66, v222
	v_sub_f32_e32 v245, v67, v222
	v_sub_f32_e32 v246, v68, v222
	v_sub_f32_e32 v247, v69, v222
	v_sub_f32_e32 v248, v70, v222
	v_sub_f32_e32 v249, v71, v222
	v_exp_f32_e32 v242, v242
	v_exp_f32_e32 v243, v243
	v_exp_f32_e32 v244, v244
	v_exp_f32_e32 v245, v245
	v_exp_f32_e32 v246, v246
	v_exp_f32_e32 v247, v247
	v_exp_f32_e32 v248, v248
	v_exp_f32_e32 v249, v249
	v_cvt_pk_bf16_f32 v64, v242, v243
	v_cvt_pk_bf16_f32 v65, v244, v245
	v_cvt_pk_bf16_f32 v66, v246, v247
	v_cvt_pk_bf16_f32 v67, v248, v249
	v_add_f32_e32 v242, v242, v243
	v_add_f32_e32 v244, v244, v245
	v_add_f32_e32 v246, v246, v247
	v_add_f32_e32 v248, v248, v249
	v_add_f32_e32 v242, v242, v244
	v_add_f32_e32 v246, v246, v248
	v_add_f32_e32 v242, v242, v246
	v_add_f32_e32 v241, v241, v242
	v_sub_f32_e32 v242, v80, v222
	v_sub_f32_e32 v243, v81, v222
	v_sub_f32_e32 v244, v82, v222
	v_sub_f32_e32 v245, v83, v222
	v_sub_f32_e32 v246, v84, v222
	v_sub_f32_e32 v247, v85, v222
	v_sub_f32_e32 v248, v86, v222
	v_sub_f32_e32 v249, v87, v222
	v_exp_f32_e32 v242, v242
	v_exp_f32_e32 v243, v243
	v_exp_f32_e32 v244, v244
	v_exp_f32_e32 v245, v245
	v_exp_f32_e32 v246, v246
	v_exp_f32_e32 v247, v247
	v_exp_f32_e32 v248, v248
	v_exp_f32_e32 v249, v249
	v_cvt_pk_bf16_f32 v72, v242, v243
	v_cvt_pk_bf16_f32 v73, v244, v245
	v_cvt_pk_bf16_f32 v74, v246, v247
	v_cvt_pk_bf16_f32 v75, v248, v249
	v_add_f32_e32 v242, v242, v243
	v_add_f32_e32 v244, v244, v245
	v_add_f32_e32 v246, v246, v247
	v_add_f32_e32 v248, v248, v249
	v_add_f32_e32 v242, v242, v244
	v_add_f32_e32 v246, v246, v248
	v_add_f32_e32 v242, v242, v246
	v_add_f32_e32 v241, v241, v242
	v_sub_f32_e32 v242, v88, v222
	v_sub_f32_e32 v243, v89, v222
	v_sub_f32_e32 v244, v90, v222
	v_sub_f32_e32 v245, v91, v222
	v_sub_f32_e32 v246, v92, v222
	v_sub_f32_e32 v247, v93, v222
	v_sub_f32_e32 v248, v94, v222
	v_sub_f32_e32 v249, v95, v222
	v_exp_f32_e32 v242, v242
	v_exp_f32_e32 v243, v243
	v_exp_f32_e32 v244, v244
	v_exp_f32_e32 v245, v245
	v_exp_f32_e32 v246, v246
	v_exp_f32_e32 v247, v247
	v_exp_f32_e32 v248, v248
	v_exp_f32_e32 v249, v249
	s_mul_i32 s0, s16, 0x4800
	v_add_u32_e32 v240, s0, v217
	ds_read_b128 v[76:79], v240 offset:51200
	ds_read_b128 v[80:83], v240 offset:51232
	ds_read_b128 v[84:87], v240 offset:55808
	ds_read_b128 v[88:91], v240 offset:55840
	ds_read_b128 v[92:95], v240 offset:60416
	ds_read_b128 v[166:169], v240 offset:60448
	ds_read_b128 v[224:227], v240 offset:65024
	ds_read_b128 v[228:231], v240 offset:65056
	v_cvt_pk_bf16_f32 v68, v242, v243
	v_cvt_pk_bf16_f32 v69, v244, v245
	v_cvt_pk_bf16_f32 v70, v246, v247
	v_cvt_pk_bf16_f32 v71, v248, v249
	v_add_f32_e32 v242, v242, v243
	v_add_f32_e32 v244, v244, v245
	v_add_f32_e32 v246, v246, v247
	v_add_f32_e32 v248, v248, v249
	v_add_f32_e32 v242, v242, v244
	v_add_f32_e32 v246, v246, v248
	v_add_f32_e32 v242, v242, v246
	v_add_f32_e32 v241, v241, v242
	s_waitcnt lgkmcnt(7)
	v_mfma_f32_32x32x16_bf16 v[0:15], v[72:75], v[76:79], v[0:15]
	s_waitcnt lgkmcnt(5)
	v_mfma_f32_32x32x16_bf16 v[48:63], v[72:75], v[84:87], v[48:63]
	s_waitcnt lgkmcnt(3)
	v_mfma_f32_32x32x16_bf16 v[32:47], v[72:75], v[92:95], v[32:47]
	s_waitcnt lgkmcnt(1)
	v_mfma_f32_32x32x16_bf16 v[16:31], v[72:75], v[224:227], v[16:31]
	ds_read_b128 v[72:75], v240 offset:51264
	ds_read_b128 v[76:79], v240 offset:55872
	ds_read_b128 v[84:87], v240 offset:60480
	ds_read_b128 v[92:95], v240 offset:65088
	v_mfma_f32_32x32x16_bf16 v[0:15], v[68:71], v[80:83], v[0:15]
	v_mfma_f32_32x32x16_bf16 v[48:63], v[68:71], v[88:91], v[48:63]
	v_mfma_f32_32x32x16_bf16 v[32:47], v[68:71], v[166:169], v[32:47]
	s_waitcnt lgkmcnt(4)
	v_mfma_f32_32x32x16_bf16 v[16:31], v[68:71], v[228:231], v[16:31]
	ds_read_b128 v[68:71], v240 offset:51296
	ds_read_b128 v[80:83], v240 offset:55904
	ds_read_b128 v[88:91], v240 offset:60512
	ds_read_b128 v[166:169], v240 offset:65120
	s_waitcnt lgkmcnt(7)
	v_mfma_f32_32x32x16_bf16 v[0:15], v[64:67], v[72:75], v[0:15]
	s_waitcnt lgkmcnt(6)
	v_mfma_f32_32x32x16_bf16 v[48:63], v[64:67], v[76:79], v[48:63]
	s_waitcnt lgkmcnt(5)
	v_mfma_f32_32x32x16_bf16 v[32:47], v[64:67], v[84:87], v[32:47]
	s_waitcnt lgkmcnt(4)
	v_mfma_f32_32x32x16_bf16 v[16:31], v[64:67], v[92:95], v[16:31]
	s_waitcnt lgkmcnt(3)
	v_mfma_f32_32x32x16_bf16 v[0:15], v[232:235], v[68:71], v[0:15]
	s_waitcnt lgkmcnt(2)
	v_mfma_f32_32x32x16_bf16 v[48:63], v[232:235], v[80:83], v[48:63]
	s_waitcnt lgkmcnt(1)
	v_mfma_f32_32x32x16_bf16 v[32:47], v[232:235], v[88:91], v[32:47]
	s_waitcnt lgkmcnt(0)
	v_mfma_f32_32x32x16_bf16 v[16:31], v[232:235], v[166:169], v[16:31]
	v_add_f32_e32 v191, v191, v241
